# attention phase: per-segment s_setprio flips removed, one static s_setprio 1 for waves 4-7 during the phase (reset to 0 at the next seam)
# baseline (speedup 1.0000x reference)
; #define LAS __attribute__((address_space(3)))
; __global__ void __launch_bounds__(512, 2) mega_fwd(Args a) {
;     ...
;         float lam;
;         { int l_o = threadIdx.x; asm volatile("" : "+v"(l_o)); const int lane = l_o & 63; const float p1 = wave_sum(a.in[6][lane] * a.in[7][lane]), p2 = wave_sum(a.in[8][lane] * a.in[9][lane]); lam = __uint_as_float(__builtin_amdgcn_readfirstlane(__float_as_uint(expf(p1) - expf(p2) + 0.2f))); }
;         unsigned* cnt_u = (unsigned*)(a.ws + WS_BAR) + 3600; unsigned* cnt_c = (unsigned*)(a.ws + WS_BAR) + 3968;
;         volatile LAS unsigned* wq = (volatile LAS unsigned*)(lds + LDS_BYTES - 128);
;         const int xq = (int)(blockIdx.x & 7);
;     ...
; #pragma unroll 1
;         for (int ustat = blockIdx.x;; ustat += G) {
;             int ucode, useq;
;             if (ATT_DYNAMIC) {
;                 __syncthreads();
;                 if (threadIdx.x == 0) wq[0] = __hip_atomic_fetch_add(cnt_u + 16 * xq, 1u, __ATOMIC_RELAXED, __HIP_MEMORY_SCOPE_AGENT);
;                 __syncthreads();
;                 const int useq8 = __builtin_amdgcn_readfirstlane((int)wq[0]);
;                 if (useq8 >= 64) break;
;                 ucode = (int)((0x809A1B2CD3E4F567ull >> (4 * (useq8 >> 2))) & 15ull);
;                 useq = (useq8 & 3) * 8 + xq;
;             } else {
;                 if (G == 256) {
;                     const int k = (int)blockIdx.x >> 5, ui = (ustat - (int)blockIdx.x) >> 8;
;                     const int nu = (k == 0) ? 1 : (k == 7 ? 3 : 2);
;                     if (ui >= nu * (1 + ((DUP_MASK >> 16) & 1))) break;
;                     const unsigned codes = (k == 0) ? 0x007u : (k == 1) ? 0x006u : (k == 2) ? 0x015u : (k == 3) ? 0x024u : (k == 4) ? 0x0D3u : (k == 5) ? 0x0BFu : (k == 6) ? 0x0CEu : 0x89Au;
;                     ucode = (int)((codes >> (4 * (ui % nu))) & 15u); useq = (int)blockIdx.x & 31;
;                 } else {
;                 if (ustat >= 512 * (1 + ((DUP_MASK >> 16) & 1))) break;
;                 const int us = ustat & 511;
;                 useq = us & 31; ucode = us < 256 ? (us >> 5) : (8 | (7 - ((us - 256) >> 5)));
.Lsm4_done:
.LBB0_553:
	s_mov_b64 exec, -1
	v_readfirstlane_b32 s98, v222
	s_cmp_lt_u32 s98, 0x100
	s_cbranch_scc1 .Lp4prio
	s_setprio 1
.Lp4prio:
	s_waitcnt lgkmcnt(0)
	v_mov_b32_e32 v0, v222
	s_barrier
	v_mbcnt_hi_u32_b32 v5, -1, v216
	v_and_b32_e32 v0, 63, v0
	v_lshlrev_b32_e32 v0, 2, v0
	global_load_dword v1, v0, s[48:49]
	global_load_dword v2, v0, s[50:51]
	global_load_dword v3, v0, s[16:17]
	global_load_dword v4, v0, s[18:19]
	v_and_b32_e32 v8, 64, v5
	v_xor_b32_e32 v9, 1, v5
	v_add_u32_e32 v8, 64, v8
	v_cmp_lt_i32_e32 vcc, v9, v8
	v_xor_b32_e32 v10, 2, v5
	v_xor_b32_e32 v11, 4, v5
	v_cndmask_b32_e32 v9, v5, v9, vcc
	v_lshlrev_b32_e32 v9, 2, v9
	v_cmp_lt_i32_e32 vcc, v10, v8
	v_xor_b32_e32 v12, 8, v5
	v_xor_b32_e32 v13, 16, v5
	v_cndmask_b32_e32 v10, v5, v10, vcc
	v_cmp_lt_i32_e32 vcc, v11, v8
	v_xor_b32_e32 v14, 32, v5
	s_mov_b32 s6, 0x3fb8aa3b
	v_cndmask_b32_e32 v11, v5, v11, vcc
	v_cmp_lt_i32_e32 vcc, v12, v8
	s_add_u32 s8, s58, 0xb200000
	s_addc_u32 s9, s59, 0
	v_cndmask_b32_e32 v12, v5, v12, vcc
	v_cmp_lt_i32_e32 vcc, v13, v8
	s_ashr_i32 s70, s2, 5
	s_mov_b32 s1, 0xc2ce8ed0
	v_cndmask_b32_e32 v13, v5, v13, vcc
	v_cmp_lt_i32_e32 vcc, v14, v8
	v_lshlrev_b32_e32 v8, 2, v10
	v_lshlrev_b32_e32 v10, 2, v11
	v_cndmask_b32_e32 v5, v5, v14, vcc
	v_lshlrev_b32_e32 v223, 2, v5
	v_lshlrev_b32_e32 v224, 2, v13
	s_cmp_eq_u32 s70, 7
	s_cselect_b32 s10, 3, 2
	s_cmp_gt_u32 s2, 31
	s_mov_b32 s0, 0x42b17218
	s_cselect_b64 s[12:13], -1, 0
	s_mov_b32 s11, 0
	v_mov_b32_e32 v6, 0x7f800000
	v_cndmask_b32_e64 v211, 0, 1, s[12:13]
	s_and_b64 s[12:13], s[12:13], exec
	s_movk_i32 s7, 0xce
	s_mov_b32 s3, s11
	s_cselect_b32 s71, s10, 1
	s_cmp_eq_u32 s70, 6
	s_cselect_b32 s80, s7, 0x89a
	s_lshl_b64 s[12:13], s[2:3], 17
	v_cvt_f32_ubyte0_e32 v212, s71
	s_add_u32 s3, s58, s12
	v_rcp_iflag_f32_e32 v213, v212
	v_mov_b32_e32 v7, 0x3e4ccccd
	s_addc_u32 s7, s59, s13
	s_mov_b32 s16, 2.0
	s_mov_b32 s18, 4.0
	s_mov_b32 s42, 0x40c00000
	s_add_u32 s44, s3, 0xc200000
	v_mov_b32_e32 v0, 0
	s_movk_i32 s23, 0x1000
	s_mov_b32 s50, 0x42fc0000
	s_movk_i32 s51, 0x110
	s_movk_i32 s68, 0x90
	s_mov_b32 s17, 0x40400000
	s_mov_b32 s19, 0x40a00000
	s_mov_b32 s43, 0x40e00000
	s_mov_b32 s69, 0x41000000
	v_mov_b32_e32 v210, 0x358637bd
	s_addc_u32 s45, s7, 0
	s_add_i32 s3, 0, 0x12000
	s_add_i32 s81, 0, 0x12800
	v_mov_b32_e32 v214, 0xff800000
	v_mov_b32_e32 v215, 0x42800000
	v_mov_b32_e32 v216, 0xfffff000
	v_mov_b32_e32 v217, 0x1000
	v_mov_b32_e32 v218, 0xf149f2ca
	s_mov_b32 s82, s2
	s_waitcnt vmcnt(2)
	v_mul_f32_e32 v15, v1, v2
	ds_bpermute_b32 v15, v9, v15
	s_waitcnt vmcnt(0)
	v_mul_f32_e32 v16, v3, v4
	ds_bpermute_b32 v9, v9, v16
	s_waitcnt lgkmcnt(1)
	v_fmac_f32_e32 v15, v1, v2
	ds_bpermute_b32 v1, v8, v15
	s_waitcnt lgkmcnt(1)
	v_fmac_f32_e32 v9, v3, v4
	ds_bpermute_b32 v2, v8, v9
	v_lshlrev_b32_e32 v3, 2, v12
	s_waitcnt lgkmcnt(1)
	v_add_f32_e32 v1, v15, v1
	ds_bpermute_b32 v4, v10, v1
	s_waitcnt lgkmcnt(1)
	v_add_f32_e32 v2, v9, v2
	ds_bpermute_b32 v5, v10, v2
	s_waitcnt lgkmcnt(1)
	v_add_f32_e32 v1, v1, v4
	ds_bpermute_b32 v4, v3, v1
	s_waitcnt lgkmcnt(1)
	v_add_f32_e32 v2, v2, v5
	ds_bpermute_b32 v3, v3, v2
	s_waitcnt lgkmcnt(1)
	v_add_f32_e32 v1, v1, v4
	s_waitcnt lgkmcnt(0)
	v_add_f32_e32 v2, v2, v3
	ds_bpermute_b32 v3, v224, v1
	ds_bpermute_b32 v4, v224, v2
	s_waitcnt lgkmcnt(1)
	v_add_f32_e32 v1, v1, v3
	s_waitcnt lgkmcnt(0)
	v_add_f32_e32 v2, v2, v4
	ds_bpermute_b32 v3, v223, v1
	ds_bpermute_b32 v4, v223, v2
	s_waitcnt lgkmcnt(1)
	v_add_f32_e32 v1, v1, v3
	s_waitcnt lgkmcnt(0)
	v_add_f32_e32 v2, v2, v4
	v_mul_f32_e32 v3, 0x3fb8aa3b, v1
	v_mul_f32_e32 v4, 0x3fb8aa3b, v2
	v_fma_f32 v5, v1, s6, -v3
	v_rndne_f32_e32 v8, v3
	v_fma_f32 v9, v2, s6, -v4
	v_rndne_f32_e32 v10, v4
	v_fmac_f32_e32 v5, 0x32a5705f, v1
	v_sub_f32_e32 v3, v3, v8
	v_fmac_f32_e32 v9, 0x32a5705f, v2
	v_sub_f32_e32 v4, v4, v10
	v_add_f32_e32 v3, v3, v5
	v_cvt_i32_f32_e32 v8, v8
	v_add_f32_e32 v4, v4, v9
	v_exp_f32_e32 v3, v3
	v_cvt_i32_f32_e32 v10, v10
	v_exp_f32_e32 v4, v4
	v_cmp_ngt_f32_e32 vcc, s1, v1
	v_ldexp_f32 v3, v3, v8
	v_ldexp_f32 v4, v4, v10
	v_cndmask_b32_e32 v3, 0, v3, vcc
	v_cmp_ngt_f32_e32 vcc, s1, v2
	s_nop 1
	v_cndmask_b32_e32 v4, 0, v4, vcc
	v_cmp_nlt_f32_e32 vcc, s0, v1
	s_nop 1
	v_cndmask_b32_e32 v1, v6, v3, vcc
	v_cmp_nlt_f32_e32 vcc, s0, v2
	s_nop 1
	v_cndmask_b32_e32 v2, v6, v4, vcc
	v_sub_f32_e32 v1, v1, v2
	s_nop 0
	v_readfirstlane_b32 s0, v1
	s_nop 1
	v_add_f32_e32 v148, s0, v7
	v_mov_b32_e32 v149, v148
	s_branch .LBB0_557

; template <int DH, bool MOBA>
; __device__ __forceinline__ void flash_pass(LAS unsigned char* lds, const bf16_t* qrow, const bf16_t* kbase, const bf16_t* vtbase, int q0, int qblk, float sl2, unsigned sel, f32x16 (&o)[4], int tid) {
;     ...
;             const float fb = sl2 * (float)(kv0 + 8 * hi - qpos) - m_run;
;             const int thr = qpos - kv0 - 8 * hi;
;             const bool need = (diag && kv0 + 63 > qw0) || (MOBA && !diag && !__all(mysel ? 1 : 0));
;             int thr_eff = diag ? thr : 4096;
;             if (MOBA) thr_eff = (!diag && !mysel) ? -4096 : thr_eff;
;             constexpr int NQK = DH / 16, PER = 16 / NQK;
;             {
;                 const float fb0 = fb, fb1 = fb + sl2 * 16.0f;
; #pragma unroll
;                 for (int r = 0; r < 16; ++r) s[0][r] = ((r >> 3) ? fb1 : fb0) + sl2 * (float)(r & 7);
;             }
;             const float fb2 = fb + sl2 * 32.0f, fb3 = fb + sl2 * 48.0f;
;             __builtin_amdgcn_s_setprio(1);
; #pragma unroll
;             for (int g0 = 0; g0 < NQK; g0 += 4) {
;                 bf16x8 kf[4];
; #pragma unroll
;                 for (int j4 = 0; j4 < 4; ++j4) kf[j4] = *(const LAS bf16x8*)(Kb + kfo + (g0 + j4) * 32);
; #pragma unroll
;                 for (int j4 = 0; j4 < 4; ++j4) { const int d0 = g0 + j4;
;                     s[0] = MFMA32(kf[j4], qf[d0], s[0]);
; #pragma unroll
;                     for (int j = 0; j < PER; ++j) { const int r = d0 * PER + j; s[1][r] = ((r >> 3) ? fb3 : fb2) + sl2 * (float)(r & 7); }
;                 }
;                 __builtin_amdgcn_sched_barrier(0);
;             }
;             __builtin_amdgcn_s_setprio(0);
;             if (need) {
; #pragma unroll
;                 for (int r = 0; r < 16; ++r) s[0][r] = (16 * (r >> 3) + (r & 7) > thr_eff) ? ATT_NEG : s[0][r];
;             }
;             float mx = fmaxf(fmaxf(s[0][0], s[0][1]), s[0][2]);
; #pragma unroll
;             for (int r = 3; r < 15; r += 2) mx = fmaxf(fmaxf(mx, s[0][r]), s[0][r + 1]);
;             mx = fmaxf(mx, s[0][15]);
;             __builtin_amdgcn_sched_barrier(0);
;             __builtin_amdgcn_s_setprio(1);
; #pragma unroll
;             for (int g0 = 0; g0 < NQK; g0 += 4) {
;                 bf16x8 kf[4];
; #pragma unroll
;                 for (int j4 = 0; j4 < 4; ++j4) kf[j4] = *(const LAS bf16x8*)(Kb + kfo + 32 * KP + (g0 + j4) * 32);
; #pragma unroll
.LBB0_676:
	v_or_b32_e32 v14, s66, v154
	v_sub_u32_e32 v15, v14, v189
	v_cvt_f32_i32_e32 v15, v15
	v_sub_u32_e32 v84, v189, v14
	s_and_b32 s14, s49, 1
	v_fma_f32 v14, v161, v15, -v1
	v_cndmask_b32_e64 v15, v216, v217, s[0:1]
	v_add_f32_e32 v80, v197, v14
	v_pk_add_f32 v[96:97], v[160:161], v[14:15] op_sel_hi:[1,0]
	v_pk_add_f32 v[98:99], v[168:169], v[14:15] op_sel_hi:[1,0]
	v_pk_add_f32 v[100:101], v[170:171], v[14:15] op_sel_hi:[1,0]
	v_pk_add_f32 v[102:103], v[172:173], v[14:15] op_sel_hi:[1,0]
	v_pk_add_f32 v[104:105], v[160:161], v[80:81] op_sel_hi:[1,0]
	v_pk_add_f32 v[106:107], v[168:169], v[80:81] op_sel_hi:[1,0]
	v_pk_add_f32 v[108:109], v[170:171], v[80:81] op_sel_hi:[1,0]
	v_pk_add_f32 v[110:111], v[172:173], v[80:81] op_sel_hi:[1,0]
	s_nop 0
	s_mul_i32 s0, s14, 0x4400
	v_add_u32_e32 v180, s0, v198
	ds_read_b128 v[80:83], v180
	s_waitcnt vmcnt(11) lgkmcnt(0)
	v_mfma_f32_32x32x16_bf16 v[96:111], v[80:83], v[112:115], v[96:111]
	ds_read_b128 v[80:83], v180 offset:32
	s_waitcnt vmcnt(10) lgkmcnt(0)
	v_mfma_f32_32x32x16_bf16 v[96:111], v[80:83], v[116:119], v[96:111]
	ds_read_b128 v[80:83], v180 offset:64
	s_waitcnt vmcnt(9) lgkmcnt(0)
	v_mfma_f32_32x32x16_bf16 v[96:111], v[80:83], v[120:123], v[96:111]
	ds_read_b128 v[80:83], v180 offset:96
	s_waitcnt vmcnt(8) lgkmcnt(0)
	v_mfma_f32_32x32x16_bf16 v[96:111], v[80:83], v[124:127], v[96:111]
	ds_read_b128 v[80:83], v180 offset:128
	s_waitcnt vmcnt(7) lgkmcnt(0)
	v_mfma_f32_32x32x16_bf16 v[96:111], v[80:83], v[128:131], v[96:111]
	ds_read_b128 v[80:83], v180 offset:160
	s_waitcnt vmcnt(6) lgkmcnt(0)
	v_mfma_f32_32x32x16_bf16 v[96:111], v[80:83], v[132:135], v[96:111]
	ds_read_b128 v[80:83], v180 offset:192
	s_waitcnt vmcnt(5) lgkmcnt(0)
	v_mfma_f32_32x32x16_bf16 v[96:111], v[80:83], v[136:139], v[96:111]
	ds_read_b128 v[80:83], v180 offset:224
	s_waitcnt vmcnt(4) lgkmcnt(0)
	v_mfma_f32_32x32x16_bf16 v[96:111], v[80:83], v[140:143], v[96:111]
	v_cndmask_b32_e64 v203, v15, v84, s[6:7]
	s_nop 0
	v_cndmask_b32_e64 v15, 0, 1, s[12:13]
	v_cmp_ne_u32_e64 s[6:7], 1, v15
	s_andn2_b64 vcc, exec, s[12:13]
	s_cbranch_vccnz .LBB0_678
	v_cmp_lt_i32_e32 vcc, -1, v203
	s_nop 4
	v_cndmask_b32_e32 v96, v218, v96, vcc
	v_cmp_lt_i32_e32 vcc, 0, v203
	s_nop 1
	v_cndmask_b32_e32 v97, v218, v97, vcc
	v_cmp_lt_i32_e32 vcc, 1, v203
	s_nop 1
	v_cndmask_b32_e32 v98, v218, v98, vcc
	v_cmp_lt_i32_e32 vcc, 2, v203
	s_nop 1
	v_cndmask_b32_e32 v99, v218, v99, vcc
	v_cmp_lt_i32_e32 vcc, 3, v203
	s_nop 1
	v_cndmask_b32_e32 v100, v218, v100, vcc
	v_cmp_lt_i32_e32 vcc, 4, v203
	s_nop 1
	v_cndmask_b32_e32 v101, v218, v101, vcc
	v_cmp_lt_i32_e32 vcc, 5, v203
	s_nop 1
	v_cndmask_b32_e32 v102, v218, v102, vcc
	v_cmp_lt_i32_e32 vcc, 6, v203
	s_nop 1
	v_cndmask_b32_e32 v103, v218, v103, vcc
	v_cmp_lt_i32_e32 vcc, 15, v203
	s_nop 1
	v_cndmask_b32_e32 v104, v218, v104, vcc
	v_cmp_lt_i32_e32 vcc, 16, v203
	s_nop 1
	v_cndmask_b32_e32 v105, v218, v105, vcc
	v_cmp_lt_i32_e32 vcc, 17, v203
	s_nop 1
	v_cndmask_b32_e32 v106, v218, v106, vcc
	v_cmp_lt_i32_e32 vcc, 18, v203
	s_nop 1
	v_cndmask_b32_e32 v107, v218, v107, vcc
	v_cmp_lt_i32_e32 vcc, 19, v203
	s_nop 1
	v_cndmask_b32_e32 v108, v218, v108, vcc
	v_cmp_lt_i32_e32 vcc, 20, v203
	s_nop 1
	v_cndmask_b32_e32 v109, v218, v109, vcc
	v_cmp_lt_i32_e32 vcc, 21, v203
	s_nop 1
	v_cndmask_b32_e32 v110, v218, v110, vcc
	v_cmp_lt_i32_e32 vcc, 22, v203
	s_nop 1
	v_cndmask_b32_e32 v111, v218, v111, vcc
.LBB0_678:
	v_add_f32_e32 v86, v199, v14
	v_add_f32_e32 v14, v200, v14
	v_pk_add_f32 v[80:81], v[160:161], v[86:87] op_sel_hi:[1,0]
	v_pk_add_f32 v[82:83], v[168:169], v[86:87] op_sel_hi:[1,0]
	v_pk_add_f32 v[84:85], v[170:171], v[86:87] op_sel_hi:[1,0]
	v_pk_add_f32 v[86:87], v[172:173], v[86:87] op_sel_hi:[1,0]
	v_pk_add_f32 v[88:89], v[160:161], v[14:15] op_sel_hi:[1,0]
	v_pk_add_f32 v[90:91], v[168:169], v[14:15] op_sel_hi:[1,0]
	v_pk_add_f32 v[92:93], v[170:171], v[14:15] op_sel_hi:[1,0]
	v_pk_add_f32 v[94:95], v[172:173], v[14:15] op_sel_hi:[1,0]
	s_nop 0
	ds_read_b128 v[174:177], v180 offset:8704
	ds_read_b128 v[182:185], v180 offset:8736
	ds_read_b128 v[204:207], v180 offset:8768
	ds_read_b128 v[226:229], v180 offset:8800
	v_exp_f32_e32 v14, v96
	v_exp_f32_e32 v15, v97
	s_waitcnt lgkmcnt(3)
	v_mfma_f32_32x32x16_bf16 v[80:95], v[174:177], v[112:115], v[80:95]
	s_waitcnt lgkmcnt(2)
	v_mfma_f32_32x32x16_bf16 v[80:95], v[182:185], v[116:119], v[80:95]
	v_exp_f32_e32 v174, v98
	v_exp_f32_e32 v175, v99
	s_waitcnt lgkmcnt(1)
	v_mfma_f32_32x32x16_bf16 v[80:95], v[204:207], v[120:123], v[80:95]
	v_exp_f32_e32 v176, v100
	v_exp_f32_e32 v177, v101
	s_waitcnt lgkmcnt(0)
	v_mfma_f32_32x32x16_bf16 v[80:95], v[226:229], v[124:127], v[80:95]
	v_exp_f32_e32 v178, v102
	v_exp_f32_e32 v179, v103
	ds_read_b128 v[182:185], v180 offset:8832
	ds_read_b128 v[204:207], v180 offset:8864
	ds_read_b128 v[226:229], v180 offset:8896
	ds_read_b128 v[230:233], v180 offset:8928
	v_exp_f32_e32 v180, v104
	s_waitcnt lgkmcnt(3)
	v_mfma_f32_32x32x16_bf16 v[80:95], v[182:185], v[128:131], v[80:95]
	v_exp_f32_e32 v181, v105
	s_waitcnt lgkmcnt(2)
	v_mfma_f32_32x32x16_bf16 v[80:95], v[204:207], v[132:135], v[80:95]
	v_exp_f32_e32 v182, v106
	v_exp_f32_e32 v183, v107
	s_waitcnt lgkmcnt(1)
	v_mfma_f32_32x32x16_bf16 v[80:95], v[226:229], v[136:139], v[80:95]
	v_exp_f32_e32 v184, v108
	v_exp_f32_e32 v185, v109
	s_waitcnt lgkmcnt(0)
	v_mfma_f32_32x32x16_bf16 v[80:95], v[230:233], v[140:143], v[80:95]
	v_exp_f32_e32 v186, v110
	v_exp_f32_e32 v187, v111
	s_nop 0
	s_and_b64 vcc, exec, s[6:7]
	s_cbranch_vccnz .LBB0_680
	v_cmp_lt_i32_e32 vcc, 31, v203
	s_nop 5
	v_cndmask_b32_e32 v80, v218, v80, vcc
	v_cmp_lt_i32_e32 vcc, 32, v203
	s_nop 1
	v_cndmask_b32_e32 v81, v218, v81, vcc
	v_cmp_lt_i32_e32 vcc, 33, v203
	s_nop 1
	v_cndmask_b32_e32 v82, v218, v82, vcc
	v_cmp_lt_i32_e32 vcc, 34, v203
	s_nop 1
	v_cndmask_b32_e32 v83, v218, v83, vcc
	v_cmp_lt_i32_e32 vcc, 35, v203
	s_nop 1
	v_cndmask_b32_e32 v84, v218, v84, vcc
	v_cmp_lt_i32_e32 vcc, 36, v203
	s_nop 1
	v_cndmask_b32_e32 v85, v218, v85, vcc
	v_cmp_lt_i32_e32 vcc, 37, v203
	s_nop 1
	v_cndmask_b32_e32 v86, v218, v86, vcc
	v_cmp_lt_i32_e32 vcc, 38, v203
	s_nop 1
	v_cndmask_b32_e32 v87, v218, v87, vcc
	v_cmp_lt_i32_e32 vcc, 47, v203
	s_nop 1
	v_cndmask_b32_e32 v88, v218, v88, vcc
	v_cmp_lt_i32_e32 vcc, 48, v203
	s_nop 1
	v_cndmask_b32_e32 v89, v218, v89, vcc
	v_cmp_lt_i32_e32 vcc, 49, v203
	s_nop 1
	v_cndmask_b32_e32 v90, v218, v90, vcc
	v_cmp_lt_i32_e32 vcc, 50, v203
	s_nop 1
	v_cndmask_b32_e32 v91, v218, v91, vcc
	v_cmp_lt_i32_e32 vcc, 51, v203
	s_nop 1
	v_cndmask_b32_e32 v92, v218, v92, vcc
	v_cmp_lt_i32_e32 vcc, 52, v203
	s_nop 1
	v_cndmask_b32_e32 v93, v218, v93, vcc
	v_cmp_lt_i32_e32 vcc, 53, v203
	s_nop 1
	v_cndmask_b32_e32 v94, v218, v94, vcc
	v_cmp_lt_i32_e32 vcc, 54, v203
	s_nop 1
	v_cndmask_b32_e32 v95, v218, v95, vcc

; #define LAS __attribute__((address_space(3)))
; #define MFMA32(a, b, c) __builtin_amdgcn_mfma_f32_32x32x16_bf16((a), (b), (c), 0, 0, 0)
; #define PACK8(S, B) __builtin_bit_cast(bf16x8, (u32x4){cvt_pk_bf16(S[B], S[B + 1]), cvt_pk_bf16(S[B + 2], S[B + 3]), cvt_pk_bf16(S[B + 4], S[B + 5]), cvt_pk_bf16(S[B + 6], S[B + 7])})
; template <int DH, bool MOBA>
; __device__ __forceinline__ void flash_pass(LAS unsigned char* lds, const bf16_t* qrow, const bf16_t* kbase, const bf16_t* vtbase, int q0, int qblk, float sl2, unsigned sel, f32x16 (&o)[4], int tid) {
;     ...
;             float lsum = 0.f;
; #pragma unroll
;             for (int r = 0; r < 16; ++r) lsum += s[0][r];
;             bf16x8 pb[4];
;             pb[0] = PACK8(s[0], 0); pb[1] = PACK8(s[0], 8);
;             __builtin_amdgcn_sched_barrier(0);
;             __builtin_amdgcn_s_setprio(1);
; #pragma unroll
;             for (int c = 0; c < 2; ++c) {
;                 bf16x8 vf[4];
; #pragma unroll
;                 for (int d = 0; d < 4; ++d) vf[d] = *(const LAS bf16x8*)(Vb + vfo + d * 32 * ATT_VP + c * 32);
; #pragma unroll
;                 for (int d = 0; d < 4; ++d) { o[d] = MFMA32(vf[d], pb[c], o[d]);
;                     s[1][(c * 4 + d) * 2] = __builtin_amdgcn_exp2f(s[1][(c * 4 + d) * 2]); s[1][(c * 4 + d) * 2 + 1] = __builtin_amdgcn_exp2f(s[1][(c * 4 + d) * 2 + 1]);
;                     __builtin_amdgcn_sched_barrier(0); }
;             }
;             pb[2] = PACK8(s[1], 0); pb[3] = PACK8(s[1], 8);
;             __builtin_amdgcn_sched_barrier(0);
; #pragma unroll
;             for (int c = 2; c < 4; ++c) {
;                 bf16x8 vf[4];
; #pragma unroll
;                 for (int d = 0; d < 4; ++d) vf[d] = *(const LAS bf16x8*)(Vb + vfo + d * 32 * ATT_VP + c * 32);
; #pragma unroll
;                 for (int d = 0; d < 4; ++d) { o[d] = MFMA32(vf[d], pb[c], o[d]);
;                     lsum += s[1][((c - 2) * 4 + d) * 2] + s[1][((c - 2) * 4 + d) * 2 + 1];
;                     __builtin_amdgcn_sched_barrier(0); }
;             }
;             __builtin_amdgcn_s_setprio(0);
;             l_run += lsum;
.LBB0_682:
	s_mulk_i32 s14, 0x4800
	v_cvt_pk_bf16_f32 v96, v14, v15
	v_cvt_pk_bf16_f32 v97, v174, v175
	v_cvt_pk_bf16_f32 v98, v176, v177
	v_cvt_pk_bf16_f32 v99, v178, v179
	v_cvt_pk_bf16_f32 v100, v180, v181
	v_cvt_pk_bf16_f32 v101, v182, v183
	v_cvt_pk_bf16_f32 v102, v184, v185
	v_cvt_pk_bf16_f32 v103, v186, v187
	s_nop 0
	v_add_u32_e32 v203, s14, v201
	ds_read_b128 v[104:107], v203 offset:34816
	ds_read_b128 v[108:111], v203 offset:39424
	ds_read_b128 v[204:207], v203 offset:44032
	ds_read_b128 v[226:229], v203 offset:48640
	v_exp_f32_e32 v209, v80
	s_waitcnt lgkmcnt(3)
	v_mfma_f32_32x32x16_bf16 v[64:79], v[104:107], v[96:99], v[64:79]
	v_exp_f32_e32 v231, v81
	s_waitcnt lgkmcnt(2)
	v_mfma_f32_32x32x16_bf16 v[48:63], v[108:111], v[96:99], v[48:63]
	v_exp_f32_e32 v208, v82
	v_exp_f32_e32 v230, v83
	s_waitcnt lgkmcnt(1)
	v_mfma_f32_32x32x16_bf16 v[32:47], v[204:207], v[96:99], v[32:47]
	v_exp_f32_e32 v109, v84
	v_exp_f32_e32 v111, v85
	s_waitcnt lgkmcnt(0)
	v_mfma_f32_32x32x16_bf16 v[16:31], v[226:229], v[96:99], v[16:31]
	v_exp_f32_e32 v108, v86
	v_exp_f32_e32 v110, v87
	ds_read_b128 v[80:83], v203 offset:34848
	ds_read_b128 v[84:87], v203 offset:39456
	ds_read_b128 v[96:99], v203 offset:44064
	ds_read_b128 v[104:107], v203 offset:48672
	v_exp_f32_e32 v205, v88
	s_waitcnt lgkmcnt(3)
	v_mfma_f32_32x32x16_bf16 v[64:79], v[80:83], v[100:103], v[64:79]
	v_exp_f32_e32 v207, v89
	s_waitcnt lgkmcnt(2)
	v_mfma_f32_32x32x16_bf16 v[48:63], v[84:87], v[100:103], v[48:63]
	v_exp_f32_e32 v204, v90
	v_exp_f32_e32 v206, v91
	s_waitcnt lgkmcnt(1)
	v_mfma_f32_32x32x16_bf16 v[32:47], v[96:99], v[100:103], v[32:47]
	v_exp_f32_e32 v227, v92
	v_exp_f32_e32 v229, v93
	s_waitcnt lgkmcnt(0)
	v_mfma_f32_32x32x16_bf16 v[16:31], v[104:107], v[100:103], v[16:31]
	v_exp_f32_e32 v226, v94
	v_exp_f32_e32 v228, v95
	v_add_f32_e32 v14, 0, v14
	v_add_f32_e32 v14, v15, v14
	v_add_f32_e32 v14, v174, v14
	v_add_f32_e32 v14, v175, v14
	v_add_f32_e32 v14, v176, v14
	v_add_f32_e32 v14, v177, v14
	v_add_f32_e32 v14, v178, v14
	v_add_f32_e32 v14, v179, v14
	v_add_f32_e32 v14, v180, v14
	v_add_f32_e32 v14, v181, v14
	v_add_f32_e32 v14, v182, v14
	v_add_f32_e32 v14, v183, v14
	v_add_f32_e32 v14, v184, v14
	v_add_f32_e32 v14, v185, v14
	v_add_f32_e32 v14, v186, v14
	v_add_f32_e32 v98, v187, v14
	ds_read_b128 v[80:83], v203 offset:34880
	ds_read_b128 v[84:87], v203 offset:39488
	ds_read_b128 v[88:91], v203 offset:44096
	ds_read_b128 v[92:95], v203 offset:48704
	v_pk_add_f32 v[14:15], v[208:209], v[230:231]
	v_cvt_pk_bf16_f32 v96, v209, v231
	v_add_f32_e32 v15, v15, v98
	v_cvt_pk_bf16_f32 v97, v208, v230
	v_add_f32_e32 v100, v14, v15
	v_cvt_pk_bf16_f32 v98, v109, v111
	v_cvt_pk_bf16_f32 v99, v108, v110
	v_pk_add_f32 v[14:15], v[108:109], v[110:111]
	s_waitcnt lgkmcnt(3)
	v_mfma_f32_32x32x16_bf16 v[64:79], v[80:83], v[96:99], v[64:79]
	v_add_f32_e32 v15, v15, v100
	v_add_f32_e32 v100, v14, v15
	s_waitcnt lgkmcnt(2)
	v_mfma_f32_32x32x16_bf16 v[48:63], v[84:87], v[96:99], v[48:63]
	s_waitcnt lgkmcnt(1)
	v_mfma_f32_32x32x16_bf16 v[32:47], v[88:91], v[96:99], v[32:47]
	s_waitcnt lgkmcnt(0)
	v_mfma_f32_32x32x16_bf16 v[16:31], v[92:95], v[96:99], v[16:31]
	ds_read_b128 v[80:83], v203 offset:34912
	ds_read_b128 v[84:87], v203 offset:39520
	ds_read_b128 v[88:91], v203 offset:44128
	ds_read_b128 v[92:95], v203 offset:48736
	v_add_f32_e64 v14, v204, v206
	v_add_f32_e64 v15, v205, v207
	v_cvt_pk_bf16_f32 v96, v205, v207
	v_add_f32_e32 v15, v15, v100
	v_cvt_pk_bf16_f32 v97, v204, v206
	v_add_f32_e32 v100, v14, v15
	v_cvt_pk_bf16_f32 v98, v227, v229
	v_cvt_pk_bf16_f32 v99, v226, v228
	v_pk_add_f32 v[14:15], v[226:227], v[228:229]
	s_waitcnt lgkmcnt(3)
	v_mfma_f32_32x32x16_bf16 v[64:79], v[80:83], v[96:99], v[64:79]
	v_add_f32_e32 v15, v15, v100
	v_add_f32_e32 v14, v14, v15
	s_waitcnt lgkmcnt(2)
	v_mfma_f32_32x32x16_bf16 v[48:63], v[84:87], v[96:99], v[48:63]
	s_waitcnt lgkmcnt(1)
	v_mfma_f32_32x32x16_bf16 v[32:47], v[88:91], v[96:99], v[32:47]
	s_waitcnt lgkmcnt(0)
	v_mfma_f32_32x32x16_bf16 v[16:31], v[92:95], v[96:99], v[16:31]
	s_nop 0
	v_add_f32_e32 v202, v202, v14

; template <int DH, bool MOBA>
; __device__ __forceinline__ void flash_pass(LAS unsigned char* lds, const bf16_t* qrow, const bf16_t* kbase, const bf16_t* vtbase, int q0, int qblk, float sl2, unsigned sel, f32x16 (&o)[4], int tid) {
;     ...
;         const bool mysel = MOBA ? (((sel >> blk) & 1u) != 0u) : true;
;         if (MOBA && !diag) { if (!__any(mysel ? 1 : 0)) active = false; }
;         if (active) {
;             const LAS unsigned char* Kb = lds + buf * ATT_LDS_KB; const LAS unsigned char* Vb = lds + ATT_LDS_V0 + buf * ATT_LDS_VB;
;             f32x16 s[2];
;             const float fb = sl2 * (float)(kv0 + 8 * hi - qpos) - m_run;
;             const int thr = qpos - kv0 - 8 * hi;
;             const bool need = (diag && kv0 + 63 > qw0) || (MOBA && !diag && !__all(mysel ? 1 : 0));
;             int thr_eff = diag ? thr : 4096;
;             if (MOBA) thr_eff = (!diag && !mysel) ? -4096 : thr_eff;
;             constexpr int NQK = DH / 16, PER = 16 / NQK;
;             {
;                 const float fb0 = fb, fb1 = fb + sl2 * 16.0f;
; #pragma unroll
;                 for (int r = 0; r < 16; ++r) s[0][r] = ((r >> 3) ? fb1 : fb0) + sl2 * (float)(r & 7);
;             }
;             const float fb2 = fb + sl2 * 32.0f, fb3 = fb + sl2 * 48.0f;
;             __builtin_amdgcn_s_setprio(1);
; #pragma unroll
;             for (int g0 = 0; g0 < NQK; g0 += 4) {
;                 bf16x8 kf[4];
; #pragma unroll
;                 for (int j4 = 0; j4 < 4; ++j4) kf[j4] = *(const LAS bf16x8*)(Kb + kfo + (g0 + j4) * 32);
; #pragma unroll
;                 for (int j4 = 0; j4 < 4; ++j4) { const int d0 = g0 + j4;
;                     s[0] = MFMA32(kf[j4], qf[d0], s[0]);
; #pragma unroll
;                     for (int j = 0; j < PER; ++j) { const int r = d0 * PER + j; s[1][r] = ((r >> 3) ? fb3 : fb2) + sl2 * (float)(r & 7); }
;                 }
;                 __builtin_amdgcn_sched_barrier(0);
;             }
;             __builtin_amdgcn_s_setprio(0);
;             if (need) {
; #pragma unroll
;                 for (int r = 0; r < 16; ++r) s[0][r] = (16 * (r >> 3) + (r & 7) > thr_eff) ? ATT_NEG : s[0][r];
;             }
;             float mx = fmaxf(fmaxf(s[0][0], s[0][1]), s[0][2]);
; #pragma unroll
;             for (int r = 3; r < 15; r += 2) mx = fmaxf(fmaxf(mx, s[0][r]), s[0][r + 1]);
;             mx = fmaxf(mx, s[0][15]);
.LBB0_690:
	s_lshr_b32 s6, s12, 2
	s_add_i32 s85, s12, 1
	s_cmp_lt_u32 s85, s46
	s_cselect_b32 s7, s85, s12
	s_lshl_b32 s10, s7, 6
	v_add_u32_e32 v66, s10, v136
	v_ashrrev_i32_e32 v67, 31, v66
	v_lshlrev_b64 v[66:67], 14, v[66:67]
	v_lshl_add_u64 v[66:67], v[164:165], 0, v[66:67]
	v_lshl_add_u64 v[68:69], s[10:11], 1, v[140:141]
	v_lshl_add_u64 v[70:71], v[68:69], 0, v[142:143]
	global_load_dwordx4 v[122:125], v[66:67], off offset:2048
	global_load_dwordx4 v[114:117], v[70:71], off
	v_lshl_add_u64 v[66:67], v[68:69], 0, v[146:147]
	global_load_dwordx4 v[118:121], v[66:67], off
	s_cmp_lg_u32 s6, s83
	s_cselect_b64 s[6:7], -1, 0
	s_cmp_le_i32 s49, s48
	s_cselect_b64 s[66:67], -1, 0
	s_or_b64 s[66:67], s[6:7], s[66:67]
	s_andn2_b64 vcc, exec, s[66:67]
	s_cbranch_vccnz .LBB0_698
	v_add_u32_e32 v66, s49, v190
	v_cvt_f32_i32_e32 v66, v66
	s_and_b32 s10, s12, 1
	s_add_i32 s12, s49, 63
	s_cmp_le_i32 s12, s47
	v_fma_f32 v74, v155, v66, -v1
	s_cselect_b64 s[12:13], -1, 0
	v_add_f32_e32 v66, v182, v74
	s_or_b64 s[12:13], s[6:7], s[12:13]
	v_pk_add_f32 v[82:83], v[154:155], v[74:75] op_sel_hi:[1,0]
	v_pk_add_f32 v[84:85], v[156:157], v[74:75] op_sel_hi:[1,0]
	v_pk_add_f32 v[86:87], v[158:159], v[74:75] op_sel_hi:[1,0]
	v_pk_add_f32 v[88:89], v[160:161], v[74:75] op_sel_hi:[1,0]
	v_pk_add_f32 v[90:91], v[154:155], v[66:67] op_sel_hi:[1,0]
	v_pk_add_f32 v[92:93], v[156:157], v[66:67] op_sel_hi:[1,0]
	v_pk_add_f32 v[94:95], v[158:159], v[66:67] op_sel_hi:[1,0]
	v_pk_add_f32 v[96:97], v[160:161], v[66:67] op_sel_hi:[1,0]
	s_nop 0
	s_mul_i32 s66, s10, 0x4400
	v_add_u32_e32 v166, s66, v183
	ds_read_b128 v[66:69], v166
	v_cndmask_b32_e64 v192, v189, v217, s[6:7]
	s_waitcnt lgkmcnt(0)
	v_mfma_f32_32x32x16_bf16 v[82:97], v[66:69], v[98:101], v[82:97]
	ds_read_b128 v[66:69], v166 offset:32
	s_waitcnt lgkmcnt(0)
	v_mfma_f32_32x32x16_bf16 v[82:97], v[66:69], v[102:105], v[82:97]
	ds_read_b128 v[66:69], v166 offset:64
	s_waitcnt lgkmcnt(0)
	v_mfma_f32_32x32x16_bf16 v[82:97], v[66:69], v[106:109], v[82:97]
	ds_read_b128 v[66:69], v166 offset:96
	s_waitcnt lgkmcnt(0)
	v_mfma_f32_32x32x16_bf16 v[82:97], v[66:69], v[110:113], v[82:97]
	s_nop 0
	s_and_b64 vcc, exec, s[12:13]
	s_cbranch_vccnz .LBB0_693
	v_cmp_lt_i32_e32 vcc, -1, v192
	s_nop 7
	v_cndmask_b32_e32 v82, v218, v82, vcc
	v_cmp_lt_i32_e32 vcc, 0, v192
	s_nop 1
	v_cndmask_b32_e32 v83, v218, v83, vcc
	v_cmp_lt_i32_e32 vcc, 1, v192
	s_nop 1
	v_cndmask_b32_e32 v84, v218, v84, vcc
	v_cmp_lt_i32_e32 vcc, 2, v192
	s_nop 1
	v_cndmask_b32_e32 v85, v218, v85, vcc
	v_cmp_lt_i32_e32 vcc, 3, v192
	s_nop 1
	v_cndmask_b32_e32 v86, v218, v86, vcc
	v_cmp_lt_i32_e32 vcc, 4, v192
	s_nop 1
	v_cndmask_b32_e32 v87, v218, v87, vcc
	v_cmp_lt_i32_e32 vcc, 5, v192
	s_nop 1
	v_cndmask_b32_e32 v88, v218, v88, vcc
	v_cmp_lt_i32_e32 vcc, 6, v192
	s_nop 1
	v_cndmask_b32_e32 v89, v218, v89, vcc
	v_cmp_lt_i32_e32 vcc, 15, v192
	s_nop 1
	v_cndmask_b32_e32 v90, v218, v90, vcc
	v_cmp_lt_i32_e32 vcc, 16, v192
	s_nop 1
	v_cndmask_b32_e32 v91, v218, v91, vcc
	v_cmp_lt_i32_e32 vcc, 17, v192
	s_nop 1
	v_cndmask_b32_e32 v92, v218, v92, vcc
	v_cmp_lt_i32_e32 vcc, 18, v192
	s_nop 1
	v_cndmask_b32_e32 v93, v218, v93, vcc
	v_cmp_lt_i32_e32 vcc, 19, v192
	s_nop 1
	v_cndmask_b32_e32 v94, v218, v94, vcc
	v_cmp_lt_i32_e32 vcc, 20, v192
	s_nop 1
	v_cndmask_b32_e32 v95, v218, v95, vcc
	v_cmp_lt_i32_e32 vcc, 21, v192
	s_nop 1
	v_cndmask_b32_e32 v96, v218, v96, vcc
	v_cmp_lt_i32_e32 vcc, 22, v192
	s_nop 1
	v_cndmask_b32_e32 v97, v218, v97, vcc
.LBB0_693:
	v_add_f32_e32 v72, v184, v74
	v_add_f32_e32 v80, v185, v74
	v_pk_add_f32 v[66:67], v[154:155], v[72:73] op_sel_hi:[1,0]
	v_pk_add_f32 v[68:69], v[156:157], v[72:73] op_sel_hi:[1,0]
	v_pk_add_f32 v[70:71], v[158:159], v[72:73] op_sel_hi:[1,0]
	v_pk_add_f32 v[72:73], v[160:161], v[72:73] op_sel_hi:[1,0]
	v_pk_add_f32 v[74:75], v[154:155], v[80:81] op_sel_hi:[1,0]
	v_pk_add_f32 v[76:77], v[156:157], v[80:81] op_sel_hi:[1,0]
	v_pk_add_f32 v[78:79], v[158:159], v[80:81] op_sel_hi:[1,0]
	v_pk_add_f32 v[80:81], v[160:161], v[80:81] op_sel_hi:[1,0]
	s_xor_b64 s[6:7], s[12:13], -1
	s_nop 0
	ds_read_b128 v[170:173], v166 offset:4608
	ds_read_b128 v[174:177], v166 offset:4640
	ds_read_b128 v[178:181], v166 offset:4672
	ds_read_b128 v[194:197], v166 offset:4704
	v_exp_f32_e32 v166, v82
	s_waitcnt lgkmcnt(3)
	v_mfma_f32_32x32x16_bf16 v[66:81], v[170:173], v[98:101], v[66:81]
	v_exp_f32_e32 v167, v83
	v_exp_f32_e32 v168, v84
	v_exp_f32_e32 v169, v85
	s_waitcnt lgkmcnt(2)
	v_mfma_f32_32x32x16_bf16 v[66:81], v[174:177], v[102:105], v[66:81]
	v_exp_f32_e32 v170, v86
	v_exp_f32_e32 v171, v87
	v_exp_f32_e32 v172, v88
	v_exp_f32_e32 v173, v89
	s_waitcnt lgkmcnt(1)
	v_mfma_f32_32x32x16_bf16 v[66:81], v[178:181], v[106:109], v[66:81]
	v_exp_f32_e32 v174, v90
	v_exp_f32_e32 v175, v91
	v_exp_f32_e32 v176, v92
	v_exp_f32_e32 v177, v93
	s_waitcnt lgkmcnt(0)
	v_mfma_f32_32x32x16_bf16 v[66:81], v[194:197], v[110:113], v[66:81]
	v_exp_f32_e32 v178, v94
	v_exp_f32_e32 v179, v95
	v_exp_f32_e32 v180, v96
	v_exp_f32_e32 v181, v97
	s_nop 0
	s_andn2_b64 vcc, exec, s[6:7]
	s_cbranch_vccnz .LBB0_695
	v_cmp_lt_i32_e32 vcc, 31, v192
	s_nop 3
	v_cndmask_b32_e32 v66, v218, v66, vcc
	v_cmp_lt_i32_e32 vcc, 32, v192
	s_nop 1
	v_cndmask_b32_e32 v67, v218, v67, vcc
	v_cmp_lt_i32_e32 vcc, 33, v192
	s_nop 1
	v_cndmask_b32_e32 v68, v218, v68, vcc
	v_cmp_lt_i32_e32 vcc, 34, v192
	s_nop 1
	v_cndmask_b32_e32 v69, v218, v69, vcc
	v_cmp_lt_i32_e32 vcc, 35, v192
	s_nop 1
	v_cndmask_b32_e32 v70, v218, v70, vcc
	v_cmp_lt_i32_e32 vcc, 36, v192
	s_nop 1
	v_cndmask_b32_e32 v71, v218, v71, vcc
	v_cmp_lt_i32_e32 vcc, 37, v192
	s_nop 1
	v_cndmask_b32_e32 v72, v218, v72, vcc
	v_cmp_lt_i32_e32 vcc, 38, v192
	s_nop 1
	v_cndmask_b32_e32 v73, v218, v73, vcc
	v_cmp_lt_i32_e32 vcc, 47, v192
	s_nop 1
	v_cndmask_b32_e32 v74, v218, v74, vcc
	v_cmp_lt_i32_e32 vcc, 48, v192
	s_nop 1
	v_cndmask_b32_e32 v75, v218, v75, vcc
	v_cmp_lt_i32_e32 vcc, 49, v192
	s_nop 1
	v_cndmask_b32_e32 v76, v218, v76, vcc
	v_cmp_lt_i32_e32 vcc, 50, v192
	s_nop 1
	v_cndmask_b32_e32 v77, v218, v77, vcc
	v_cmp_lt_i32_e32 vcc, 51, v192
	s_nop 1
	v_cndmask_b32_e32 v78, v218, v78, vcc
	v_cmp_lt_i32_e32 vcc, 52, v192
	s_nop 1
	v_cndmask_b32_e32 v79, v218, v79, vcc
	v_cmp_lt_i32_e32 vcc, 53, v192
	s_nop 1
	v_cndmask_b32_e32 v80, v218, v80, vcc
	v_cmp_lt_i32_e32 vcc, 54, v192
	s_nop 1
	v_cndmask_b32_e32 v81, v218, v81, vcc

; #define LAS __attribute__((address_space(3)))
; #define MFMA32(a, b, c) __builtin_amdgcn_mfma_f32_32x32x16_bf16((a), (b), (c), 0, 0, 0)
; #define PACK8(S, B) __builtin_bit_cast(bf16x8, (u32x4){cvt_pk_bf16(S[B], S[B + 1]), cvt_pk_bf16(S[B + 2], S[B + 3]), cvt_pk_bf16(S[B + 4], S[B + 5]), cvt_pk_bf16(S[B + 6], S[B + 7])})
; template <int DH, bool MOBA>
; __device__ __forceinline__ void flash_pass(LAS unsigned char* lds, const bf16_t* qrow, const bf16_t* kbase, const bf16_t* vtbase, int q0, int qblk, float sl2, unsigned sel, f32x16 (&o)[4], int tid) {
;     ...
;             float lsum = 0.f;
; #pragma unroll
;             for (int r = 0; r < 16; ++r) lsum += s[0][r];
;             bf16x8 pb[4];
;             pb[0] = PACK8(s[0], 0); pb[1] = PACK8(s[0], 8);
;             __builtin_amdgcn_sched_barrier(0);
;             __builtin_amdgcn_s_setprio(1);
; #pragma unroll
;             for (int c = 0; c < 2; ++c) {
;                 bf16x8 vf[4];
; #pragma unroll
;                 for (int d = 0; d < 4; ++d) vf[d] = *(const LAS bf16x8*)(Vb + vfo + d * 32 * ATT_VP + c * 32);
; #pragma unroll
;                 for (int d = 0; d < 4; ++d) { o[d] = MFMA32(vf[d], pb[c], o[d]);
;                     s[1][(c * 4 + d) * 2] = __builtin_amdgcn_exp2f(s[1][(c * 4 + d) * 2]); s[1][(c * 4 + d) * 2 + 1] = __builtin_amdgcn_exp2f(s[1][(c * 4 + d) * 2 + 1]);
;                     __builtin_amdgcn_sched_barrier(0); }
;             }
;             pb[2] = PACK8(s[1], 0); pb[3] = PACK8(s[1], 8);
;             __builtin_amdgcn_sched_barrier(0);
; #pragma unroll
;             for (int c = 2; c < 4; ++c) {
;                 bf16x8 vf[4];
; #pragma unroll
;                 for (int d = 0; d < 4; ++d) vf[d] = *(const LAS bf16x8*)(Vb + vfo + d * 32 * ATT_VP + c * 32);
; #pragma unroll
;                 for (int d = 0; d < 4; ++d) { o[d] = MFMA32(vf[d], pb[c], o[d]);
;                     lsum += s[1][((c - 2) * 4 + d) * 2] + s[1][((c - 2) * 4 + d) * 2 + 1];
;                     __builtin_amdgcn_sched_barrier(0); }
;             }
;             __builtin_amdgcn_s_setprio(0);
;             l_run += lsum;
.LBB0_697:
	s_mulk_i32 s10, 0x4800
	v_cvt_pk_bf16_f32 v82, v166, v167
	v_cvt_pk_bf16_f32 v83, v168, v169
	v_cvt_pk_bf16_f32 v84, v170, v171
	v_cvt_pk_bf16_f32 v85, v172, v173
	v_cvt_pk_bf16_f32 v86, v174, v175
	v_cvt_pk_bf16_f32 v87, v176, v177
	v_cvt_pk_bf16_f32 v88, v178, v179
	v_cvt_pk_bf16_f32 v89, v180, v181
	s_nop 0
	v_add_u32_e32 v204, s10, v186
	ds_read_b128 v[90:93], v204 offset:34816
	ds_read_b128 v[94:97], v204 offset:39424
	ds_read_b128 v[192:195], v204 offset:44032
	ds_read_b128 v[196:199], v204 offset:48640
	v_exp_f32_e32 v201, v66
	s_waitcnt lgkmcnt(3)
	v_mfma_f32_32x32x16_bf16 v[50:65], v[90:93], v[82:85], v[50:65]
	v_exp_f32_e32 v203, v67
	s_waitcnt lgkmcnt(2)
	v_mfma_f32_32x32x16_bf16 v[34:49], v[94:97], v[82:85], v[34:49]
	v_exp_f32_e32 v200, v68
	v_exp_f32_e32 v202, v69
	s_waitcnt lgkmcnt(1)
	v_mfma_f32_32x32x16_bf16 v[18:33], v[192:195], v[82:85], v[18:33]
	v_exp_f32_e32 v95, v70
	v_exp_f32_e32 v97, v71
	s_waitcnt lgkmcnt(0)
	v_mfma_f32_32x32x16_bf16 v[2:17], v[196:199], v[82:85], v[2:17]
	v_exp_f32_e32 v94, v72
	v_exp_f32_e32 v96, v73
	ds_read_b128 v[66:69], v204 offset:34848
	ds_read_b128 v[70:73], v204 offset:39456
	ds_read_b128 v[82:85], v204 offset:44064
	ds_read_b128 v[90:93], v204 offset:48672
	v_exp_f32_e32 v193, v74
	s_waitcnt lgkmcnt(3)
	v_mfma_f32_32x32x16_bf16 v[50:65], v[66:69], v[86:89], v[50:65]
	v_exp_f32_e32 v195, v75
	s_waitcnt lgkmcnt(2)
	v_mfma_f32_32x32x16_bf16 v[34:49], v[70:73], v[86:89], v[34:49]
	v_exp_f32_e32 v192, v76
	v_exp_f32_e32 v194, v77
	s_waitcnt lgkmcnt(1)
	v_mfma_f32_32x32x16_bf16 v[18:33], v[82:85], v[86:89], v[18:33]
	v_exp_f32_e32 v197, v78
	v_exp_f32_e32 v199, v79
	s_waitcnt lgkmcnt(0)
	v_mfma_f32_32x32x16_bf16 v[2:17], v[90:93], v[86:89], v[2:17]
	v_exp_f32_e32 v196, v80
	v_exp_f32_e32 v198, v81
	v_add_f32_e32 v66, 0, v166
	v_add_f32_e32 v66, v167, v66
	v_add_f32_e32 v66, v168, v66
	v_add_f32_e32 v66, v169, v66
	v_add_f32_e32 v66, v170, v66
	v_add_f32_e32 v66, v171, v66
	v_add_f32_e32 v66, v172, v66
	v_add_f32_e32 v66, v173, v66
	v_add_f32_e32 v66, v174, v66
	v_add_f32_e32 v66, v175, v66
	v_add_f32_e32 v66, v176, v66
	v_add_f32_e32 v66, v177, v66
	v_add_f32_e32 v66, v178, v66
	v_add_f32_e32 v66, v179, v66
	v_add_f32_e32 v66, v180, v66
	v_add_f32_e32 v86, v181, v66
	ds_read_b128 v[66:69], v204 offset:34880
	ds_read_b128 v[70:73], v204 offset:39488
	ds_read_b128 v[74:77], v204 offset:44096
	ds_read_b128 v[78:81], v204 offset:48704
	v_pk_add_f32 v[84:85], v[200:201], v[202:203]
	v_cvt_pk_bf16_f32 v82, v201, v203
	v_add_f32_e32 v85, v85, v86
	v_cvt_pk_bf16_f32 v83, v200, v202
	v_add_f32_e32 v86, v84, v85
	v_cvt_pk_bf16_f32 v84, v95, v97
	v_cvt_pk_bf16_f32 v85, v94, v96
	s_waitcnt lgkmcnt(3)
	s_nop 0
	v_mfma_f32_32x32x16_bf16 v[50:65], v[66:69], v[82:85], v[50:65]
	v_add_f32_e64 v66, v94, v96
	v_add_f32_e64 v67, v95, v97
	v_add_f32_e32 v67, v67, v86
	v_add_f32_e32 v86, v66, v67
	s_waitcnt lgkmcnt(2)
	v_mfma_f32_32x32x16_bf16 v[34:49], v[70:73], v[82:85], v[34:49]
	s_waitcnt lgkmcnt(1)
	v_mfma_f32_32x32x16_bf16 v[18:33], v[74:77], v[82:85], v[18:33]
	s_waitcnt lgkmcnt(0)
	v_mfma_f32_32x32x16_bf16 v[2:17], v[78:81], v[82:85], v[2:17]
	ds_read_b128 v[66:69], v204 offset:34912
	ds_read_b128 v[70:73], v204 offset:39520
	ds_read_b128 v[74:77], v204 offset:44128
	ds_read_b128 v[78:81], v204 offset:48736
	v_add_f32_e64 v84, v192, v194
	v_add_f32_e64 v85, v193, v195
	v_cvt_pk_bf16_f32 v82, v193, v195
	v_add_f32_e32 v85, v85, v86
	v_cvt_pk_bf16_f32 v83, v192, v194
	v_add_f32_e32 v86, v84, v85
	v_cvt_pk_bf16_f32 v84, v197, v199
	v_cvt_pk_bf16_f32 v85, v196, v198
	s_waitcnt lgkmcnt(3)
	s_nop 0
	v_mfma_f32_32x32x16_bf16 v[50:65], v[66:69], v[82:85], v[50:65]
	v_add_f32_e64 v66, v196, v198
	v_add_f32_e64 v67, v197, v199
	v_add_f32_e32 v67, v67, v86
	v_add_f32_e32 v66, v66, v67
	s_waitcnt lgkmcnt(2)
	v_mfma_f32_32x32x16_bf16 v[34:49], v[70:73], v[82:85], v[34:49]
	s_waitcnt lgkmcnt(1)
	v_mfma_f32_32x32x16_bf16 v[18:33], v[74:77], v[82:85], v[18:33]
	s_waitcnt lgkmcnt(0)
	v_mfma_f32_32x32x16_bf16 v[2:17], v[78:81], v[82:85], v[2:17]
	s_nop 0
	v_add_f32_e32 v191, v191, v66

; __device__ __forceinline__ unsigned xb_ld(unsigned* p)              { return __hip_atomic_load(p, __ATOMIC_RELAXED, __HIP_MEMORY_SCOPE_AGENT); }
; __device__ __forceinline__ unsigned xb_add(unsigned* p, unsigned v) { return __hip_atomic_fetch_add(p, v, __ATOMIC_RELAXED, __HIP_MEMORY_SCOPE_AGENT); }
; #define XB_SPIN(cond, bar) do { unsigned _sp = 0; while (cond) { __builtin_amdgcn_s_sleep(1); \
;     if ((++_sp & 255u) == 0u) { if (xb_ld(&(bar)[XB_TMO])) break; if (_sp > XB_SPIN_CAP) { atomicAdd(&(bar)[XB_TMO], 1u); break; } } } } while (0)
; __device__ __forceinline__ void xcd_barrier(const XcdBarrier& b) {
;     asm volatile("s_waitcnt vmcnt(0)" ::: "memory");
;     __syncthreads();
;     if (threadIdx.x == 0) {
;         unsigned* bar = b.bar;
;         __builtin_amdgcn_s_waitcnt(0);
;         unsigned nloc = b.st[0], nx = b.st[1];
;         if (nloc == 0u) { xcd_barrier_complete(bar, b.x, nloc, nx); b.st[0] = nloc; b.st[1] = nx; }
;         const unsigned old = xb_add(&bar[XB_XSUB(b.x)], 1u);
;         const unsigned gen = old / nloc;
;         if (old + 1u == (gen + 1u) * nloc) {
;             __builtin_amdgcn_fence(__ATOMIC_RELEASE, "agent");
;             asm volatile("s_waitcnt vmcnt(0)" ::: "memory");
;             const unsigned og = xb_add(&bar[XB_TOP], 1u);
;             const unsigned tg = og / nx;
;             if (og + 1u == (tg + 1u) * nx) xb_add(&bar[XB_TOPGEN], 1u);
;             else XB_SPIN(xb_ld(&bar[XB_TOPGEN]) == tg, bar);
;             __builtin_amdgcn_fence(__ATOMIC_ACQUIRE, "agent");
;             xb_add(&bar[XB_XGEN(b.x)], 1u);
;             asm volatile("s_waitcnt vmcnt(0)" ::: "memory");
;         } else {
;             XB_SPIN(xb_ld(&bar[XB_XGEN(b.x)]) == gen, bar);
;             __builtin_amdgcn_fence(__ATOMIC_ACQUIRE, "agent");
;             asm volatile("s_waitcnt vmcnt(0)" ::: "memory");
;         }
;     }
;     __syncthreads();
; }
.LBB0_715:
	s_setprio 0
	s_waitcnt vmcnt(0) lgkmcnt(0)
	s_barrier
	v_readfirstlane_b32 s98, v222
	s_nop 3
	s_cmp_lg_u32 s98, 0
	s_cbranch_scc1 .Lsm5_done
	v_mov_b32_e32 v0, 0x23fc0
	ds_read_b64 v[2:3], v0
	v_readlane_b32 s99, v252, 3
	s_add_u32 s100, s58, 0x507000
	s_addc_u32 s101, s59, 0
	s_lshl_b32 s99, s99, 8
	v_mov_b32_e32 v0, s99
	v_mov_b32_e32 v1, 1
	s_mov_b64 exec, 1
	s_nop 1
	global_atomic_add v4, v0, v1, s[100:101] sc0
	s_waitcnt vmcnt(0) lgkmcnt(0)
	v_readfirstlane_b32 s99, v4
	v_readfirstlane_b32 vcc_lo, v2
	v_readfirstlane_b32 vcc_hi, v3
	s_add_u32 s100, s58, 0x500080
	s_addc_u32 s101, s59, 0
	v_mov_b32_e32 v0, 0
	s_add_u32 s99, s99, 1
	s_mul_i32 s98, vcc_lo, 4
	s_cmp_lg_u32 s99, s98
	s_cbranch_scc1 .Lsm5_nl
	buffer_wbl2 sc1
	s_waitcnt vmcnt(0)
	buffer_inv sc1
	s_waitcnt vmcnt(0)
	global_atomic_add v0, v1, s[100:101]
	s_branch .Lsm5_ld
